# s_setprio 3 for the DN/RW scan waves (prep waves stay at 0)
# speedup vs baseline: 1.0156x; 1.0095x over previous
.LBB0_850:
	s_or_b64 exec, exec, s[16:17]
	s_waitcnt lgkmcnt(0)
	s_barrier
	s_and_saveexec_b64 s[6:7], vcc
	s_xor_b64 s[16:17], exec, s[6:7]
	s_cbranch_execz .LBB0_1083
	s_setprio 3
	v_readlane_b32 s2, v255, 2
	s_add_u32 s2, s14, s2
	v_readlane_b32 s4, v253, 59
	s_addc_u32 s3, s15, 0
	s_waitcnt vmcnt(4)
	v_lshlrev_b32_e32 v5, 3, v13
	s_waitcnt vmcnt(3)
	v_bfe_u32 v6, v14, 3, 3
	v_readlane_b32 s8, v253, 58
	s_lshl_b32 s4, s4, 1
	s_add_u32 s6, s2, s4
	s_waitcnt vmcnt(2)
	v_or3_b32 v7, v5, s8, v6
	s_addc_u32 s7, s3, 0
	v_lshlrev_b32_e32 v0, 1, v7
	v_and_b32_e32 v4, 7, v14
	v_lshl_add_u64 v[2:3], s[6:7], 0, v[0:1]
	s_mov_b64 s[2:3], 0x11435800
	v_add_u32_e32 v0, s8, v5
	v_mov_b32_e32 v84, 0
	v_lshl_add_u64 v[82:83], v[2:3], 0, s[2:3]
	v_lshlrev_b32_e32 v100, 5, v4
	v_lshlrev_b32_e32 v101, 2, v7
	s_mov_b32 s4, 0
	v_cmp_eq_u32_e64 s[44:45], 0, v4
	v_add_lshl_u32 v102, v0, v6, 2
	v_mov_b32_e32 v85, v84
	v_mov_b32_e32 v86, v84
	v_mov_b32_e32 v87, v84
	v_mov_b32_e32 v88, v84
	v_mov_b32_e32 v89, v84
	v_mov_b32_e32 v90, v84
	v_mov_b32_e32 v91, v84
	s_waitcnt vmcnt(0)
	s_branch .LBB0_853

.LBB0_897:
	s_or_b64 exec, exec, s[14:15]
	s_waitcnt lgkmcnt(0)
	s_barrier
	s_and_saveexec_b64 s[6:7], s[44:45]
	s_xor_b64 s[14:15], exec, s[6:7]
	s_cbranch_execz .LBB0_920
	s_setprio 3
	v_readlane_b32 s2, v255, 3
	s_add_u32 s2, s12, s2
	s_addc_u32 s3, s13, 0
	v_lshlrev_b32_e32 v0, 4, v75
	s_waitcnt vmcnt(21)
	v_bfe_u32 v5, v74, 2, 4
	s_lshl_b32 s4, s23, 1
	s_waitcnt vmcnt(20)
	v_and_or_b32 v6, v0, 48, v5
	s_add_u32 s6, s2, s4
	s_addc_u32 s7, s3, 0
	v_lshlrev_b32_e32 v0, 1, v6
	v_lshl_add_u64 v[2:3], s[6:7], 0, v[0:1]
	s_mov_b64 s[2:3], 0x10235800
	v_lshl_add_u64 v[76:77], v[2:3], 0, s[2:3]
	v_lshlrev_b32_e32 v0, 2, v5
	s_movk_i32 s2, 0xc0
	v_and_b32_e32 v4, 3, v74
	v_and_or_b32 v96, v74, s2, v0
	v_mov_b32_e32 v74, 0
	v_lshlrev_b32_e32 v94, 6, v4
	v_lshlrev_b32_e32 v95, 2, v6
	s_mov_b32 s4, 0
	v_cmp_eq_u32_e64 s[44:45], 0, v4
	v_add_u32_e32 v97, 0x520, v96
	v_mov_b32_e32 v75, v74
	v_mov_b32_e32 v78, v74
	v_mov_b32_e32 v79, v74
	v_mov_b32_e32 v80, v74
	v_mov_b32_e32 v81, v74
	v_mov_b32_e32 v82, v74
	v_mov_b32_e32 v83, v74
	v_mov_b32_e32 v84, v74
	v_mov_b32_e32 v85, v74
	v_mov_b32_e32 v86, v74
	v_mov_b32_e32 v87, v74
	v_mov_b32_e32 v88, v74
	v_mov_b32_e32 v89, v74
	v_mov_b32_e32 v90, v74
	v_mov_b32_e32 v91, v74
	s_waitcnt vmcnt(0)
	s_branch .LBB0_900

.LBB0_957:
	s_setprio 0
	s_or_b64 exec, exec, s[14:15]
	s_waitcnt vmcnt(0)
	s_waitcnt lgkmcnt(0)
	s_barrier
	s_mov_b64 s[14:15], -1

.LBB0_1112:
	s_setprio 0
	s_or_b64 exec, exec, s[16:17]
	s_waitcnt vmcnt(0)
	s_waitcnt lgkmcnt(0)
	s_barrier
	s_mov_b64 s[14:15], -1
	s_and_b64 vcc, exec, s[12:13]
	s_cbranch_vccnz .LBB0_875
	s_branch .LBB0_958
